# v20 plus in-proj rope-tile epilogue: next row rope table prefetched (double buffer, counted waits), lane exchanges batched, store drains removed
# speedup vs baseline: 1.0115x; 1.0005x over previous
;     __device__ __forceinline__ void operator()(const f32x4 (&acc)[2][2][4][2], const Unit& u, int wr, int wc, int fr, int fq) const {
;     ...
;                 if (ropewave) { const float* rp = rope + (size_t)(row & 8191) * 16;
; #pragma unroll
;                     for (int k = 0; k < 4; ++k) cs[k] = *(const f32x4*)(rp + 4 * k); }
; #pragma unroll
;                 for (int bj = 0; bj < 2; ++bj) {
;                     f32x4 v0 = acc[ai][bj][m][0], v1 = acc[ai][bj][m][1];
;                     if (ropewave) {
;                         float v[8] = {v0[0], v0[1], v0[2], v0[3], v1[0], v1[1], v1[2], v1[3]};
; #pragma unroll
;                         for (int j = 0; j < 8; ++j) {
;                             const float p = __shfl_xor(v[j], 16);
;                             const float c = cs[j >> 1][(j & 1) * 2], s = cs[j >> 1][(j & 1) * 2 + 1];
;                             const float nv = v[j] * c + sgn * p * s;
;                             v[j] = (fq < 2) ? nv : v[j];
;                         }
;                         v0 = (f32x4){v[0], v[1], v[2], v[3]}; v1 = (f32x4){v[4], v[5], v[6], v[7]};
.LBB0_183:
	v_readlane_b32 s94, v254, 51
	s_andn2_b64 vcc, exec, s[2:3]
	v_readlane_b32 s95, v254, 52
	v_readlane_b32 s96, v254, 53
	s_cbranch_vccnz .LBB0_185
	v_or_b32_e32 v206, 16, v154
	v_lshlrev_b32_e32 v206, 6, v206
	v_and_b32_e32 v206, 0x7ffc0, v206
	global_load_dwordx4 v[202:205], v206, s[66:67]
	global_load_dwordx4 v[198:201], v206, s[66:67] offset:16
	global_load_dwordx4 v[194:197], v206, s[66:67] offset:32
	global_load_dwordx4 v[190:193], v206, s[66:67] offset:48
	v_and_b32_e32 v206, 64, v237
	v_xor_b32_e32 v207, 16, v237
	v_add_u32_e32 v206, 64, v206
	v_cmp_lt_i32_e32 vcc, v207, v206
	s_nop 1
	v_cndmask_b32_e32 v207, v237, v207, vcc
	v_lshlrev_b32_e32 v207, 2, v207
	ds_bpermute_b32 v178, v207, v140
	ds_bpermute_b32 v179, v207, v141
	ds_bpermute_b32 v180, v207, v142
	ds_bpermute_b32 v181, v207, v143
	ds_bpermute_b32 v182, v207, v136
	ds_bpermute_b32 v183, v207, v137
	ds_bpermute_b32 v184, v207, v138
	ds_bpermute_b32 v185, v207, v139
	s_waitcnt lgkmcnt(0)
	s_waitcnt vmcnt(4)
	v_cndmask_b32_e64 v187, v178, -v178, s[36:37]
	v_mov_b32_e32 v186, v140
	v_pk_mul_f32 v[186:187], v[36:37], v[186:187]
	s_nop 0
	v_add_f32_e32 v186, v186, v187
	v_cndmask_b32_e64 v140, v140, v186, s[38:39]
	v_cndmask_b32_e64 v189, v179, -v179, s[36:37]
	v_mov_b32_e32 v188, v141
	v_pk_mul_f32 v[188:189], v[38:39], v[188:189]
	s_nop 0
	v_add_f32_e32 v188, v188, v189
	v_cndmask_b32_e64 v141, v141, v188, s[38:39]
	v_cndmask_b32_e64 v187, v180, -v180, s[36:37]
	v_mov_b32_e32 v186, v142
	v_pk_mul_f32 v[186:187], v[32:33], v[186:187]
	s_nop 0
	v_add_f32_e32 v186, v186, v187
	v_cndmask_b32_e64 v142, v142, v186, s[38:39]
	v_cndmask_b32_e64 v189, v181, -v181, s[36:37]
	v_mov_b32_e32 v188, v143
	v_pk_mul_f32 v[188:189], v[34:35], v[188:189]
	s_nop 0
	v_add_f32_e32 v188, v188, v189
	v_cndmask_b32_e64 v143, v143, v188, s[38:39]
	v_cndmask_b32_e64 v187, v182, -v182, s[36:37]
	v_mov_b32_e32 v186, v136
	v_pk_mul_f32 v[186:187], v[28:29], v[186:187]
	s_nop 0
	v_add_f32_e32 v186, v186, v187
	v_cndmask_b32_e64 v136, v136, v186, s[38:39]
	v_cndmask_b32_e64 v189, v183, -v183, s[36:37]
	v_mov_b32_e32 v188, v137
	v_pk_mul_f32 v[188:189], v[30:31], v[188:189]
	s_nop 0
	v_add_f32_e32 v188, v188, v189
	v_cndmask_b32_e64 v137, v137, v188, s[38:39]
	v_cndmask_b32_e64 v187, v184, -v184, s[36:37]
	v_mov_b32_e32 v186, v138
	v_pk_mul_f32 v[186:187], v[24:25], v[186:187]
	s_nop 0
	v_add_f32_e32 v186, v186, v187
	v_cndmask_b32_e64 v138, v138, v186, s[38:39]
	v_cndmask_b32_e64 v189, v185, -v185, s[36:37]
	v_mov_b32_e32 v188, v139
	v_pk_mul_f32 v[188:189], v[26:27], v[188:189]
	s_nop 0
	v_add_f32_e32 v188, v188, v189
	v_cndmask_b32_e64 v139, v139, v188, s[38:39]

;     __device__ __forceinline__ void operator()(const f32x4 (&acc)[2][2][4][2], const Unit& u, int wr, int wc, int fr, int fq) const {
;     ...
;                 for (int bj = 0; bj < 2; ++bj) {
;                     f32x4 v0 = acc[ai][bj][m][0], v1 = acc[ai][bj][m][1];
;                     if (ropewave) {
;                         float v[8] = {v0[0], v0[1], v0[2], v0[3], v1[0], v1[1], v1[2], v1[3]};
; #pragma unroll
;                         for (int j = 0; j < 8; ++j) {
;                             const float p = __shfl_xor(v[j], 16);
;                             const float c = cs[j >> 1][(j & 1) * 2], s = cs[j >> 1][(j & 1) * 2 + 1];
;                             const float nv = v[j] * c + sgn * p * s;
;                             v[j] = (fq < 2) ? nv : v[j];
;                         }
;                         v0 = (f32x4){v[0], v[1], v[2], v[3]}; v1 = (f32x4){v[4], v[5], v[6], v[7]};
.LBB0_192:
	v_and_b32_e32 v206, 64, v237
	v_xor_b32_e32 v207, 16, v237
	v_add_u32_e32 v206, 64, v206
	v_cmp_lt_i32_e32 vcc, v207, v206
	s_nop 1
	v_cndmask_b32_e32 v207, v237, v207, vcc
	v_lshlrev_b32_e32 v207, 2, v207
	ds_bpermute_b32 v178, v207, v132
	ds_bpermute_b32 v179, v207, v133
	ds_bpermute_b32 v180, v207, v134
	ds_bpermute_b32 v181, v207, v135
	ds_bpermute_b32 v182, v207, v128
	ds_bpermute_b32 v183, v207, v129
	ds_bpermute_b32 v184, v207, v130
	ds_bpermute_b32 v185, v207, v131
	s_waitcnt lgkmcnt(0)
	v_cndmask_b32_e64 v187, v178, -v178, s[36:37]
	v_mov_b32_e32 v186, v132
	v_pk_mul_f32 v[186:187], v[36:37], v[186:187]
	s_nop 0
	v_add_f32_e32 v186, v186, v187
	v_cndmask_b32_e64 v132, v132, v186, s[38:39]
	v_cndmask_b32_e64 v189, v179, -v179, s[36:37]
	v_mov_b32_e32 v188, v133
	v_pk_mul_f32 v[188:189], v[38:39], v[188:189]
	s_nop 0
	v_add_f32_e32 v188, v188, v189
	v_cndmask_b32_e64 v133, v133, v188, s[38:39]
	v_cndmask_b32_e64 v187, v180, -v180, s[36:37]
	v_mov_b32_e32 v186, v134
	v_pk_mul_f32 v[186:187], v[32:33], v[186:187]
	s_nop 0
	v_add_f32_e32 v186, v186, v187
	v_cndmask_b32_e64 v134, v134, v186, s[38:39]
	v_cndmask_b32_e64 v189, v181, -v181, s[36:37]
	v_mov_b32_e32 v188, v135
	v_pk_mul_f32 v[188:189], v[34:35], v[188:189]
	s_nop 0
	v_add_f32_e32 v188, v188, v189
	v_cndmask_b32_e64 v135, v135, v188, s[38:39]
	v_cndmask_b32_e64 v187, v182, -v182, s[36:37]
	v_mov_b32_e32 v186, v128
	v_pk_mul_f32 v[186:187], v[28:29], v[186:187]
	s_nop 0
	v_add_f32_e32 v186, v186, v187
	v_cndmask_b32_e64 v128, v128, v186, s[38:39]
	v_cndmask_b32_e64 v189, v183, -v183, s[36:37]
	v_mov_b32_e32 v188, v129
	v_pk_mul_f32 v[188:189], v[30:31], v[188:189]
	s_nop 0
	v_add_f32_e32 v188, v188, v189
	v_cndmask_b32_e64 v129, v129, v188, s[38:39]
	v_cndmask_b32_e64 v187, v184, -v184, s[36:37]
	v_mov_b32_e32 v186, v130
	v_pk_mul_f32 v[186:187], v[24:25], v[186:187]
	s_nop 0
	v_add_f32_e32 v186, v186, v187
	v_cndmask_b32_e64 v130, v130, v186, s[38:39]
	v_cndmask_b32_e64 v189, v185, -v185, s[36:37]
	v_mov_b32_e32 v188, v131
	v_pk_mul_f32 v[188:189], v[26:27], v[188:189]
	s_nop 0
	v_add_f32_e32 v188, v188, v189
	v_cndmask_b32_e64 v131, v131, v188, s[38:39]

;     __device__ __forceinline__ void operator()(const f32x4 (&acc)[2][2][4][2], const Unit& u, int wr, int wc, int fr, int fq) const {
;     ...
;                 if (ropewave) { const float* rp = rope + (size_t)(row & 8191) * 16;
; #pragma unroll
;                     for (int k = 0; k < 4; ++k) cs[k] = *(const f32x4*)(rp + 4 * k); }
.LBB0_197:
	s_nop 1
	v_cndmask_b32_e64 v128, 0, 1, s[8:9]
	v_cmp_ne_u32_e64 s[48:49], 1, v128
	s_andn2_b64 vcc, exec, s[8:9]
	v_or_b32_e32 v128, 16, v154
	s_cbranch_vccnz .LBB0_205
	s_and_b64 vcc, exec, s[44:45]
	s_mov_b64 s[2:3], -1
	s_movk_i32 s8, 0xe00
	s_cbranch_vccz .LBB0_206

;     __device__ __forceinline__ void operator()(const f32x4 (&acc)[2][2][4][2], const Unit& u, int wr, int wc, int fr, int fq) const {
;     ...
;                 if (ropewave) { const float* rp = rope + (size_t)(row & 8191) * 16;
; #pragma unroll
;                     for (int k = 0; k < 4; ++k) cs[k] = *(const f32x4*)(rp + 4 * k); }
; #pragma unroll
;                 for (int bj = 0; bj < 2; ++bj) {
;                     f32x4 v0 = acc[ai][bj][m][0], v1 = acc[ai][bj][m][1];
;                     if (ropewave) {
;                         float v[8] = {v0[0], v0[1], v0[2], v0[3], v1[0], v1[1], v1[2], v1[3]};
; #pragma unroll
;                         for (int j = 0; j < 8; ++j) {
;                             const float p = __shfl_xor(v[j], 16);
;                             const float c = cs[j >> 1][(j & 1) * 2], s = cs[j >> 1][(j & 1) * 2 + 1];
;                             const float nv = v[j] * c + sgn * p * s;
;                             v[j] = (fq < 2) ? nv : v[j];
;                         }
;                         v0 = (f32x4){v[0], v[1], v[2], v[3]}; v1 = (f32x4){v[4], v[5], v[6], v[7]};
.LBB0_200:
	v_or_b32_e32 v206, 32, v154
	v_lshlrev_b32_e32 v206, 6, v206
	v_and_b32_e32 v206, 0x7ffc0, v206
	global_load_dwordx4 v[36:39], v206, s[66:67]
	global_load_dwordx4 v[32:35], v206, s[66:67] offset:16
	global_load_dwordx4 v[28:31], v206, s[66:67] offset:32
	global_load_dwordx4 v[24:27], v206, s[66:67] offset:48
	v_and_b32_e32 v206, 64, v237
	v_xor_b32_e32 v207, 16, v237
	v_add_u32_e32 v206, 64, v206
	v_cmp_lt_i32_e32 vcc, v207, v206
	s_nop 1
	v_cndmask_b32_e32 v207, v237, v207, vcc
	v_lshlrev_b32_e32 v207, 2, v207
	ds_bpermute_b32 v178, v207, v124
	ds_bpermute_b32 v179, v207, v125
	ds_bpermute_b32 v180, v207, v126
	ds_bpermute_b32 v181, v207, v127
	ds_bpermute_b32 v182, v207, v120
	ds_bpermute_b32 v183, v207, v121
	ds_bpermute_b32 v184, v207, v122
	ds_bpermute_b32 v185, v207, v123
	s_waitcnt lgkmcnt(0)
	s_waitcnt vmcnt(6)
	v_cndmask_b32_e64 v187, v178, -v178, s[36:37]
	v_mov_b32_e32 v186, v124
	v_pk_mul_f32 v[186:187], v[202:203], v[186:187]
	s_nop 0
	v_add_f32_e32 v186, v186, v187
	v_cndmask_b32_e64 v124, v124, v186, s[38:39]
	v_cndmask_b32_e64 v189, v179, -v179, s[36:37]
	v_mov_b32_e32 v188, v125
	v_pk_mul_f32 v[188:189], v[204:205], v[188:189]
	s_nop 0
	v_add_f32_e32 v188, v188, v189
	v_cndmask_b32_e64 v125, v125, v188, s[38:39]
	v_cndmask_b32_e64 v187, v180, -v180, s[36:37]
	v_mov_b32_e32 v186, v126
	v_pk_mul_f32 v[186:187], v[198:199], v[186:187]
	s_nop 0
	v_add_f32_e32 v186, v186, v187
	v_cndmask_b32_e64 v126, v126, v186, s[38:39]
	v_cndmask_b32_e64 v189, v181, -v181, s[36:37]
	v_mov_b32_e32 v188, v127
	v_pk_mul_f32 v[188:189], v[200:201], v[188:189]
	s_nop 0
	v_add_f32_e32 v188, v188, v189
	v_cndmask_b32_e64 v127, v127, v188, s[38:39]
	v_cndmask_b32_e64 v187, v182, -v182, s[36:37]
	v_mov_b32_e32 v186, v120
	v_pk_mul_f32 v[186:187], v[194:195], v[186:187]
	s_nop 0
	v_add_f32_e32 v186, v186, v187
	v_cndmask_b32_e64 v120, v120, v186, s[38:39]
	v_cndmask_b32_e64 v189, v183, -v183, s[36:37]
	v_mov_b32_e32 v188, v121
	v_pk_mul_f32 v[188:189], v[196:197], v[188:189]
	s_nop 0
	v_add_f32_e32 v188, v188, v189
	v_cndmask_b32_e64 v121, v121, v188, s[38:39]
	v_cndmask_b32_e64 v187, v184, -v184, s[36:37]
	v_mov_b32_e32 v186, v122
	v_pk_mul_f32 v[186:187], v[190:191], v[186:187]
	s_nop 0
	v_add_f32_e32 v186, v186, v187
	v_cndmask_b32_e64 v122, v122, v186, s[38:39]
	v_cndmask_b32_e64 v189, v185, -v185, s[36:37]
	v_mov_b32_e32 v188, v123
	v_pk_mul_f32 v[188:189], v[192:193], v[188:189]
	s_nop 0
	v_add_f32_e32 v188, v188, v189
	v_cndmask_b32_e64 v123, v123, v188, s[38:39]

;     __device__ __forceinline__ void operator()(const f32x4 (&acc)[2][2][4][2], const Unit& u, int wr, int wc, int fr, int fq) const {
;     ...
;                 for (int bj = 0; bj < 2; ++bj) {
;                     f32x4 v0 = acc[ai][bj][m][0], v1 = acc[ai][bj][m][1];
;                     if (ropewave) {
;                         float v[8] = {v0[0], v0[1], v0[2], v0[3], v1[0], v1[1], v1[2], v1[3]};
; #pragma unroll
;                         for (int j = 0; j < 8; ++j) {
;                             const float p = __shfl_xor(v[j], 16);
;                             const float c = cs[j >> 1][(j & 1) * 2], s = cs[j >> 1][(j & 1) * 2 + 1];
;                             const float nv = v[j] * c + sgn * p * s;
;                             v[j] = (fq < 2) ? nv : v[j];
;                         }
;                         v0 = (f32x4){v[0], v[1], v[2], v[3]}; v1 = (f32x4){v[4], v[5], v[6], v[7]};
.LBB0_210:
	v_and_b32_e32 v206, 64, v237
	v_xor_b32_e32 v207, 16, v237
	v_add_u32_e32 v206, 64, v206
	v_cmp_lt_i32_e32 vcc, v207, v206
	s_nop 1
	v_cndmask_b32_e32 v207, v237, v207, vcc
	v_lshlrev_b32_e32 v207, 2, v207
	ds_bpermute_b32 v178, v207, v116
	ds_bpermute_b32 v179, v207, v117
	ds_bpermute_b32 v180, v207, v118
	ds_bpermute_b32 v181, v207, v119
	ds_bpermute_b32 v182, v207, v112
	ds_bpermute_b32 v183, v207, v113
	ds_bpermute_b32 v184, v207, v114
	ds_bpermute_b32 v185, v207, v115
	s_waitcnt lgkmcnt(0)
	v_cndmask_b32_e64 v187, v178, -v178, s[36:37]
	v_mov_b32_e32 v186, v116
	v_pk_mul_f32 v[186:187], v[202:203], v[186:187]
	s_nop 0
	v_add_f32_e32 v186, v186, v187
	v_cndmask_b32_e64 v116, v116, v186, s[38:39]
	v_cndmask_b32_e64 v189, v179, -v179, s[36:37]
	v_mov_b32_e32 v188, v117
	v_pk_mul_f32 v[188:189], v[204:205], v[188:189]
	s_nop 0
	v_add_f32_e32 v188, v188, v189
	v_cndmask_b32_e64 v117, v117, v188, s[38:39]
	v_cndmask_b32_e64 v187, v180, -v180, s[36:37]
	v_mov_b32_e32 v186, v118
	v_pk_mul_f32 v[186:187], v[198:199], v[186:187]
	s_nop 0
	v_add_f32_e32 v186, v186, v187
	v_cndmask_b32_e64 v118, v118, v186, s[38:39]
	v_cndmask_b32_e64 v189, v181, -v181, s[36:37]
	v_mov_b32_e32 v188, v119
	v_pk_mul_f32 v[188:189], v[200:201], v[188:189]
	s_nop 0
	v_add_f32_e32 v188, v188, v189
	v_cndmask_b32_e64 v119, v119, v188, s[38:39]
	v_cndmask_b32_e64 v187, v182, -v182, s[36:37]
	v_mov_b32_e32 v186, v112
	v_pk_mul_f32 v[186:187], v[194:195], v[186:187]
	s_nop 0
	v_add_f32_e32 v186, v186, v187
	v_cndmask_b32_e64 v112, v112, v186, s[38:39]
	v_cndmask_b32_e64 v189, v183, -v183, s[36:37]
	v_mov_b32_e32 v188, v113
	v_pk_mul_f32 v[188:189], v[196:197], v[188:189]
	s_nop 0
	v_add_f32_e32 v188, v188, v189
	v_cndmask_b32_e64 v113, v113, v188, s[38:39]
	v_cndmask_b32_e64 v187, v184, -v184, s[36:37]
	v_mov_b32_e32 v186, v114
	v_pk_mul_f32 v[186:187], v[190:191], v[186:187]
	s_nop 0
	v_add_f32_e32 v186, v186, v187
	v_cndmask_b32_e64 v114, v114, v186, s[38:39]
	v_cndmask_b32_e64 v189, v185, -v185, s[36:37]
	v_mov_b32_e32 v188, v115
	v_pk_mul_f32 v[188:189], v[192:193], v[188:189]
	s_nop 0
	v_add_f32_e32 v188, v188, v189
	v_cndmask_b32_e64 v115, v115, v188, s[38:39]

;     __device__ __forceinline__ void operator()(const f32x4 (&acc)[2][2][4][2], const Unit& u, int wr, int wc, int fr, int fq) const {
;     ...
;                 if (ropewave) { const float* rp = rope + (size_t)(row & 8191) * 16;
; #pragma unroll
;                     for (int k = 0; k < 4; ++k) cs[k] = *(const f32x4*)(rp + 4 * k); }
.LBB0_215:
	s_and_b64 vcc, exec, s[48:49]
	s_nop 0
	v_or_b32_e32 v112, 32, v154
	s_cbranch_vccnz .LBB0_223
	s_and_b64 vcc, exec, s[44:45]
	s_mov_b64 s[2:3], -1
	s_cbranch_vccz .LBB0_224

;     __device__ __forceinline__ void operator()(const f32x4 (&acc)[2][2][4][2], const Unit& u, int wr, int wc, int fr, int fq) const {
;     ...
;                 if (ropewave) { const float* rp = rope + (size_t)(row & 8191) * 16;
; #pragma unroll
;                     for (int k = 0; k < 4; ++k) cs[k] = *(const f32x4*)(rp + 4 * k); }
; #pragma unroll
;                 for (int bj = 0; bj < 2; ++bj) {
;                     f32x4 v0 = acc[ai][bj][m][0], v1 = acc[ai][bj][m][1];
;                     if (ropewave) {
;                         float v[8] = {v0[0], v0[1], v0[2], v0[3], v1[0], v1[1], v1[2], v1[3]};
; #pragma unroll
;                         for (int j = 0; j < 8; ++j) {
;                             const float p = __shfl_xor(v[j], 16);
;                             const float c = cs[j >> 1][(j & 1) * 2], s = cs[j >> 1][(j & 1) * 2 + 1];
;                             const float nv = v[j] * c + sgn * p * s;
;                             v[j] = (fq < 2) ? nv : v[j];
;                         }
;                         v0 = (f32x4){v[0], v[1], v[2], v[3]}; v1 = (f32x4){v[4], v[5], v[6], v[7]};
.LBB0_218:
	v_or_b32_e32 v206, 48, v154
	v_lshlrev_b32_e32 v206, 6, v206
	v_and_b32_e32 v206, 0x7ffc0, v206
	global_load_dwordx4 v[202:205], v206, s[66:67]
	global_load_dwordx4 v[198:201], v206, s[66:67] offset:16
	global_load_dwordx4 v[194:197], v206, s[66:67] offset:32
	global_load_dwordx4 v[190:193], v206, s[66:67] offset:48
	v_and_b32_e32 v206, 64, v237
	v_xor_b32_e32 v207, 16, v237
	v_add_u32_e32 v206, 64, v206
	v_cmp_lt_i32_e32 vcc, v207, v206
	s_nop 1
	v_cndmask_b32_e32 v207, v237, v207, vcc
	v_lshlrev_b32_e32 v207, 2, v207
	ds_bpermute_b32 v178, v207, v108
	ds_bpermute_b32 v179, v207, v109
	ds_bpermute_b32 v180, v207, v110
	ds_bpermute_b32 v181, v207, v111
	ds_bpermute_b32 v182, v207, v104
	ds_bpermute_b32 v183, v207, v105
	ds_bpermute_b32 v184, v207, v106
	ds_bpermute_b32 v185, v207, v107
	s_waitcnt lgkmcnt(0)
	s_waitcnt vmcnt(6)
	v_cndmask_b32_e64 v187, v178, -v178, s[36:37]
	v_mov_b32_e32 v186, v108
	v_pk_mul_f32 v[186:187], v[36:37], v[186:187]
	s_nop 0
	v_add_f32_e32 v186, v186, v187
	v_cndmask_b32_e64 v108, v108, v186, s[38:39]
	v_cndmask_b32_e64 v189, v179, -v179, s[36:37]
	v_mov_b32_e32 v188, v109
	v_pk_mul_f32 v[188:189], v[38:39], v[188:189]
	s_nop 0
	v_add_f32_e32 v188, v188, v189
	v_cndmask_b32_e64 v109, v109, v188, s[38:39]
	v_cndmask_b32_e64 v187, v180, -v180, s[36:37]
	v_mov_b32_e32 v186, v110
	v_pk_mul_f32 v[186:187], v[32:33], v[186:187]
	s_nop 0
	v_add_f32_e32 v186, v186, v187
	v_cndmask_b32_e64 v110, v110, v186, s[38:39]
	v_cndmask_b32_e64 v189, v181, -v181, s[36:37]
	v_mov_b32_e32 v188, v111
	v_pk_mul_f32 v[188:189], v[34:35], v[188:189]
	s_nop 0
	v_add_f32_e32 v188, v188, v189
	v_cndmask_b32_e64 v111, v111, v188, s[38:39]
	v_cndmask_b32_e64 v187, v182, -v182, s[36:37]
	v_mov_b32_e32 v186, v104
	v_pk_mul_f32 v[186:187], v[28:29], v[186:187]
	s_nop 0
	v_add_f32_e32 v186, v186, v187
	v_cndmask_b32_e64 v104, v104, v186, s[38:39]
	v_cndmask_b32_e64 v189, v183, -v183, s[36:37]
	v_mov_b32_e32 v188, v105
	v_pk_mul_f32 v[188:189], v[30:31], v[188:189]
	s_nop 0
	v_add_f32_e32 v188, v188, v189
	v_cndmask_b32_e64 v105, v105, v188, s[38:39]
	v_cndmask_b32_e64 v187, v184, -v184, s[36:37]
	v_mov_b32_e32 v186, v106
	v_pk_mul_f32 v[186:187], v[24:25], v[186:187]
	s_nop 0
	v_add_f32_e32 v186, v186, v187
	v_cndmask_b32_e64 v106, v106, v186, s[38:39]
	v_cndmask_b32_e64 v189, v185, -v185, s[36:37]
	v_mov_b32_e32 v188, v107
	v_pk_mul_f32 v[188:189], v[26:27], v[188:189]
	s_nop 0
	v_add_f32_e32 v188, v188, v189
	v_cndmask_b32_e64 v107, v107, v188, s[38:39]

;     __device__ __forceinline__ void operator()(const f32x4 (&acc)[2][2][4][2], const Unit& u, int wr, int wc, int fr, int fq) const {
;     ...
;                 for (int bj = 0; bj < 2; ++bj) {
;                     f32x4 v0 = acc[ai][bj][m][0], v1 = acc[ai][bj][m][1];
;                     if (ropewave) {
;                         float v[8] = {v0[0], v0[1], v0[2], v0[3], v1[0], v1[1], v1[2], v1[3]};
; #pragma unroll
;                         for (int j = 0; j < 8; ++j) {
;                             const float p = __shfl_xor(v[j], 16);
;                             const float c = cs[j >> 1][(j & 1) * 2], s = cs[j >> 1][(j & 1) * 2 + 1];
;                             const float nv = v[j] * c + sgn * p * s;
;                             v[j] = (fq < 2) ? nv : v[j];
;                         }
;                         v0 = (f32x4){v[0], v[1], v[2], v[3]}; v1 = (f32x4){v[4], v[5], v[6], v[7]};
.LBB0_228:
	v_and_b32_e32 v206, 64, v237
	v_xor_b32_e32 v207, 16, v237
	v_add_u32_e32 v206, 64, v206
	v_cmp_lt_i32_e32 vcc, v207, v206
	s_nop 1
	v_cndmask_b32_e32 v207, v237, v207, vcc
	v_lshlrev_b32_e32 v207, 2, v207
	ds_bpermute_b32 v178, v207, v100
	ds_bpermute_b32 v179, v207, v101
	ds_bpermute_b32 v180, v207, v102
	ds_bpermute_b32 v181, v207, v103
	ds_bpermute_b32 v182, v207, v96
	ds_bpermute_b32 v183, v207, v97
	ds_bpermute_b32 v184, v207, v98
	ds_bpermute_b32 v185, v207, v99
	s_waitcnt lgkmcnt(0)
	v_cndmask_b32_e64 v187, v178, -v178, s[36:37]
	v_mov_b32_e32 v186, v100
	v_pk_mul_f32 v[186:187], v[36:37], v[186:187]
	s_nop 0
	v_add_f32_e32 v186, v186, v187
	v_cndmask_b32_e64 v100, v100, v186, s[38:39]
	v_cndmask_b32_e64 v189, v179, -v179, s[36:37]
	v_mov_b32_e32 v188, v101
	v_pk_mul_f32 v[188:189], v[38:39], v[188:189]
	s_nop 0
	v_add_f32_e32 v188, v188, v189
	v_cndmask_b32_e64 v101, v101, v188, s[38:39]
	v_cndmask_b32_e64 v187, v180, -v180, s[36:37]
	v_mov_b32_e32 v186, v102
	v_pk_mul_f32 v[186:187], v[32:33], v[186:187]
	s_nop 0
	v_add_f32_e32 v186, v186, v187
	v_cndmask_b32_e64 v102, v102, v186, s[38:39]
	v_cndmask_b32_e64 v189, v181, -v181, s[36:37]
	v_mov_b32_e32 v188, v103
	v_pk_mul_f32 v[188:189], v[34:35], v[188:189]
	s_nop 0
	v_add_f32_e32 v188, v188, v189
	v_cndmask_b32_e64 v103, v103, v188, s[38:39]
	v_cndmask_b32_e64 v187, v182, -v182, s[36:37]
	v_mov_b32_e32 v186, v96
	v_pk_mul_f32 v[186:187], v[28:29], v[186:187]
	s_nop 0
	v_add_f32_e32 v186, v186, v187
	v_cndmask_b32_e64 v96, v96, v186, s[38:39]
	v_cndmask_b32_e64 v189, v183, -v183, s[36:37]
	v_mov_b32_e32 v188, v97
	v_pk_mul_f32 v[188:189], v[30:31], v[188:189]
	s_nop 0
	v_add_f32_e32 v188, v188, v189
	v_cndmask_b32_e64 v97, v97, v188, s[38:39]
	v_cndmask_b32_e64 v187, v184, -v184, s[36:37]
	v_mov_b32_e32 v186, v98
	v_pk_mul_f32 v[186:187], v[24:25], v[186:187]
	s_nop 0
	v_add_f32_e32 v186, v186, v187
	v_cndmask_b32_e64 v98, v98, v186, s[38:39]
	v_cndmask_b32_e64 v189, v185, -v185, s[36:37]
	v_mov_b32_e32 v188, v99
	v_pk_mul_f32 v[188:189], v[26:27], v[188:189]
	s_nop 0
	v_add_f32_e32 v188, v188, v189
	v_cndmask_b32_e64 v99, v99, v188, s[38:39]

;     __device__ __forceinline__ void operator()(const f32x4 (&acc)[2][2][4][2], const Unit& u, int wr, int wc, int fr, int fq) const {
;     ...
;                 if (ropewave) { const float* rp = rope + (size_t)(row & 8191) * 16;
; #pragma unroll
;                     for (int k = 0; k < 4; ++k) cs[k] = *(const f32x4*)(rp + 4 * k); }
.LBB0_233:
	s_and_b64 vcc, exec, s[48:49]
	s_nop 0
	v_or_b32_e32 v96, 48, v154
	s_cbranch_vccnz .LBB0_241
	s_and_b64 vcc, exec, s[44:45]
	s_mov_b64 s[2:3], -1
	s_cbranch_vccz .LBB0_242

;     __device__ __forceinline__ void operator()(const f32x4 (&acc)[2][2][4][2], const Unit& u, int wr, int wc, int fr, int fq) const {
;     ...
;                 if (ropewave) { const float* rp = rope + (size_t)(row & 8191) * 16;
; #pragma unroll
;                     for (int k = 0; k < 4; ++k) cs[k] = *(const f32x4*)(rp + 4 * k); }
; #pragma unroll
;                 for (int bj = 0; bj < 2; ++bj) {
;                     f32x4 v0 = acc[ai][bj][m][0], v1 = acc[ai][bj][m][1];
;                     if (ropewave) {
;                         float v[8] = {v0[0], v0[1], v0[2], v0[3], v1[0], v1[1], v1[2], v1[3]};
; #pragma unroll
;                         for (int j = 0; j < 8; ++j) {
;                             const float p = __shfl_xor(v[j], 16);
;                             const float c = cs[j >> 1][(j & 1) * 2], s = cs[j >> 1][(j & 1) * 2 + 1];
;                             const float nv = v[j] * c + sgn * p * s;
;                             v[j] = (fq < 2) ? nv : v[j];
;                         }
;                         v0 = (f32x4){v[0], v[1], v[2], v[3]}; v1 = (f32x4){v[4], v[5], v[6], v[7]};
.LBB0_236:
	v_or_b32_e32 v206, 0x80, v154
	v_lshlrev_b32_e32 v206, 6, v206
	v_and_b32_e32 v206, 0x7ffc0, v206
	global_load_dwordx4 v[36:39], v206, s[66:67]
	global_load_dwordx4 v[32:35], v206, s[66:67] offset:16
	global_load_dwordx4 v[28:31], v206, s[66:67] offset:32
	global_load_dwordx4 v[24:27], v206, s[66:67] offset:48
	v_and_b32_e32 v206, 64, v237
	v_xor_b32_e32 v207, 16, v237
	v_add_u32_e32 v206, 64, v206
	v_cmp_lt_i32_e32 vcc, v207, v206
	s_nop 1
	v_cndmask_b32_e32 v207, v237, v207, vcc
	v_lshlrev_b32_e32 v207, 2, v207
	ds_bpermute_b32 v178, v207, v92
	ds_bpermute_b32 v179, v207, v93
	ds_bpermute_b32 v180, v207, v94
	ds_bpermute_b32 v181, v207, v95
	ds_bpermute_b32 v182, v207, v88
	ds_bpermute_b32 v183, v207, v89
	ds_bpermute_b32 v184, v207, v90
	ds_bpermute_b32 v185, v207, v91
	s_waitcnt lgkmcnt(0)
	s_waitcnt vmcnt(6)
	v_cndmask_b32_e64 v187, v178, -v178, s[36:37]
	v_mov_b32_e32 v186, v92
	v_pk_mul_f32 v[186:187], v[202:203], v[186:187]
	s_nop 0
	v_add_f32_e32 v186, v186, v187
	v_cndmask_b32_e64 v92, v92, v186, s[38:39]
	v_cndmask_b32_e64 v189, v179, -v179, s[36:37]
	v_mov_b32_e32 v188, v93
	v_pk_mul_f32 v[188:189], v[204:205], v[188:189]
	s_nop 0
	v_add_f32_e32 v188, v188, v189
	v_cndmask_b32_e64 v93, v93, v188, s[38:39]
	v_cndmask_b32_e64 v187, v180, -v180, s[36:37]
	v_mov_b32_e32 v186, v94
	v_pk_mul_f32 v[186:187], v[198:199], v[186:187]
	s_nop 0
	v_add_f32_e32 v186, v186, v187
	v_cndmask_b32_e64 v94, v94, v186, s[38:39]
	v_cndmask_b32_e64 v189, v181, -v181, s[36:37]
	v_mov_b32_e32 v188, v95
	v_pk_mul_f32 v[188:189], v[200:201], v[188:189]
	s_nop 0
	v_add_f32_e32 v188, v188, v189
	v_cndmask_b32_e64 v95, v95, v188, s[38:39]
	v_cndmask_b32_e64 v187, v182, -v182, s[36:37]
	v_mov_b32_e32 v186, v88
	v_pk_mul_f32 v[186:187], v[194:195], v[186:187]
	s_nop 0
	v_add_f32_e32 v186, v186, v187
	v_cndmask_b32_e64 v88, v88, v186, s[38:39]
	v_cndmask_b32_e64 v189, v183, -v183, s[36:37]
	v_mov_b32_e32 v188, v89
	v_pk_mul_f32 v[188:189], v[196:197], v[188:189]
	s_nop 0
	v_add_f32_e32 v188, v188, v189
	v_cndmask_b32_e64 v89, v89, v188, s[38:39]
	v_cndmask_b32_e64 v187, v184, -v184, s[36:37]
	v_mov_b32_e32 v186, v90
	v_pk_mul_f32 v[186:187], v[190:191], v[186:187]
	s_nop 0
	v_add_f32_e32 v186, v186, v187
	v_cndmask_b32_e64 v90, v90, v186, s[38:39]
	v_cndmask_b32_e64 v189, v185, -v185, s[36:37]
	v_mov_b32_e32 v188, v91
	v_pk_mul_f32 v[188:189], v[192:193], v[188:189]
	s_nop 0
	v_add_f32_e32 v188, v188, v189
	v_cndmask_b32_e64 v91, v91, v188, s[38:39]

;     __device__ __forceinline__ void operator()(const f32x4 (&acc)[2][2][4][2], const Unit& u, int wr, int wc, int fr, int fq) const {
;     ...
;                 for (int bj = 0; bj < 2; ++bj) {
;                     f32x4 v0 = acc[ai][bj][m][0], v1 = acc[ai][bj][m][1];
;                     if (ropewave) {
;                         float v[8] = {v0[0], v0[1], v0[2], v0[3], v1[0], v1[1], v1[2], v1[3]};
; #pragma unroll
;                         for (int j = 0; j < 8; ++j) {
;                             const float p = __shfl_xor(v[j], 16);
;                             const float c = cs[j >> 1][(j & 1) * 2], s = cs[j >> 1][(j & 1) * 2 + 1];
;                             const float nv = v[j] * c + sgn * p * s;
;                             v[j] = (fq < 2) ? nv : v[j];
;                         }
;                         v0 = (f32x4){v[0], v[1], v[2], v[3]}; v1 = (f32x4){v[4], v[5], v[6], v[7]};
.LBB0_246:
	v_and_b32_e32 v206, 64, v237
	v_xor_b32_e32 v207, 16, v237
	v_add_u32_e32 v206, 64, v206
	v_cmp_lt_i32_e32 vcc, v207, v206
	s_nop 1
	v_cndmask_b32_e32 v207, v237, v207, vcc
	v_lshlrev_b32_e32 v207, 2, v207
	ds_bpermute_b32 v178, v207, v84
	ds_bpermute_b32 v179, v207, v85
	ds_bpermute_b32 v180, v207, v86
	ds_bpermute_b32 v181, v207, v87
	ds_bpermute_b32 v182, v207, v80
	ds_bpermute_b32 v183, v207, v81
	ds_bpermute_b32 v184, v207, v82
	ds_bpermute_b32 v185, v207, v83
	s_waitcnt lgkmcnt(0)
	v_cndmask_b32_e64 v187, v178, -v178, s[36:37]
	v_mov_b32_e32 v186, v84
	v_pk_mul_f32 v[186:187], v[202:203], v[186:187]
	s_nop 0
	v_add_f32_e32 v186, v186, v187
	v_cndmask_b32_e64 v84, v84, v186, s[38:39]
	v_cndmask_b32_e64 v189, v179, -v179, s[36:37]
	v_mov_b32_e32 v188, v85
	v_pk_mul_f32 v[188:189], v[204:205], v[188:189]
	s_nop 0
	v_add_f32_e32 v188, v188, v189
	v_cndmask_b32_e64 v85, v85, v188, s[38:39]
	v_cndmask_b32_e64 v187, v180, -v180, s[36:37]
	v_mov_b32_e32 v186, v86
	v_pk_mul_f32 v[186:187], v[198:199], v[186:187]
	s_nop 0
	v_add_f32_e32 v186, v186, v187
	v_cndmask_b32_e64 v86, v86, v186, s[38:39]
	v_cndmask_b32_e64 v189, v181, -v181, s[36:37]
	v_mov_b32_e32 v188, v87
	v_pk_mul_f32 v[188:189], v[200:201], v[188:189]
	s_nop 0
	v_add_f32_e32 v188, v188, v189
	v_cndmask_b32_e64 v87, v87, v188, s[38:39]
	v_cndmask_b32_e64 v187, v182, -v182, s[36:37]
	v_mov_b32_e32 v186, v80
	v_pk_mul_f32 v[186:187], v[194:195], v[186:187]
	s_nop 0
	v_add_f32_e32 v186, v186, v187
	v_cndmask_b32_e64 v80, v80, v186, s[38:39]
	v_cndmask_b32_e64 v189, v183, -v183, s[36:37]
	v_mov_b32_e32 v188, v81
	v_pk_mul_f32 v[188:189], v[196:197], v[188:189]
	s_nop 0
	v_add_f32_e32 v188, v188, v189
	v_cndmask_b32_e64 v81, v81, v188, s[38:39]
	v_cndmask_b32_e64 v187, v184, -v184, s[36:37]
	v_mov_b32_e32 v186, v82
	v_pk_mul_f32 v[186:187], v[190:191], v[186:187]
	s_nop 0
	v_add_f32_e32 v186, v186, v187
	v_cndmask_b32_e64 v82, v82, v186, s[38:39]
	v_cndmask_b32_e64 v189, v185, -v185, s[36:37]
	v_mov_b32_e32 v188, v83
	v_pk_mul_f32 v[188:189], v[192:193], v[188:189]
	s_nop 0
	v_add_f32_e32 v188, v188, v189
	v_cndmask_b32_e64 v83, v83, v188, s[38:39]

;     __device__ __forceinline__ void operator()(const f32x4 (&acc)[2][2][4][2], const Unit& u, int wr, int wc, int fr, int fq) const {
;     ...
;                 if (ropewave) { const float* rp = rope + (size_t)(row & 8191) * 16;
; #pragma unroll
;                     for (int k = 0; k < 4; ++k) cs[k] = *(const f32x4*)(rp + 4 * k); }
.LBB0_251:
	s_nop 1
	v_add_u32_e32 v80, 0x80, v154
	s_and_b64 vcc, exec, s[48:49]
	s_cbranch_vccnz .LBB0_259
	s_and_b64 vcc, exec, s[44:45]
	s_mov_b64 s[2:3], -1
	s_cbranch_vccz .LBB0_260

;     __device__ __forceinline__ void operator()(const f32x4 (&acc)[2][2][4][2], const Unit& u, int wr, int wc, int fr, int fq) const {
;     ...
;                 if (ropewave) { const float* rp = rope + (size_t)(row & 8191) * 16;
; #pragma unroll
;                     for (int k = 0; k < 4; ++k) cs[k] = *(const f32x4*)(rp + 4 * k); }
; #pragma unroll
;                 for (int bj = 0; bj < 2; ++bj) {
;                     f32x4 v0 = acc[ai][bj][m][0], v1 = acc[ai][bj][m][1];
;                     if (ropewave) {
;                         float v[8] = {v0[0], v0[1], v0[2], v0[3], v1[0], v1[1], v1[2], v1[3]};
; #pragma unroll
;                         for (int j = 0; j < 8; ++j) {
;                             const float p = __shfl_xor(v[j], 16);
;                             const float c = cs[j >> 1][(j & 1) * 2], s = cs[j >> 1][(j & 1) * 2 + 1];
;                             const float nv = v[j] * c + sgn * p * s;
;                             v[j] = (fq < 2) ? nv : v[j];
;                         }
;                         v0 = (f32x4){v[0], v[1], v[2], v[3]}; v1 = (f32x4){v[4], v[5], v[6], v[7]};
.LBB0_254:
	v_or_b32_e32 v206, 0x90, v154
	v_lshlrev_b32_e32 v206, 6, v206
	v_and_b32_e32 v206, 0x7ffc0, v206
	global_load_dwordx4 v[202:205], v206, s[66:67]
	global_load_dwordx4 v[198:201], v206, s[66:67] offset:16
	global_load_dwordx4 v[194:197], v206, s[66:67] offset:32
	global_load_dwordx4 v[190:193], v206, s[66:67] offset:48
	v_and_b32_e32 v206, 64, v237
	v_xor_b32_e32 v207, 16, v237
	v_add_u32_e32 v206, 64, v206
	v_cmp_lt_i32_e32 vcc, v207, v206
	s_nop 1
	v_cndmask_b32_e32 v207, v237, v207, vcc
	v_lshlrev_b32_e32 v207, 2, v207
	ds_bpermute_b32 v178, v207, v76
	ds_bpermute_b32 v179, v207, v77
	ds_bpermute_b32 v180, v207, v78
	ds_bpermute_b32 v181, v207, v79
	ds_bpermute_b32 v182, v207, v72
	ds_bpermute_b32 v183, v207, v73
	ds_bpermute_b32 v184, v207, v74
	ds_bpermute_b32 v185, v207, v75
	s_waitcnt lgkmcnt(0)
	s_waitcnt vmcnt(6)
	v_cndmask_b32_e64 v187, v178, -v178, s[36:37]
	v_mov_b32_e32 v186, v76
	v_pk_mul_f32 v[186:187], v[36:37], v[186:187]
	s_nop 0
	v_add_f32_e32 v186, v186, v187
	v_cndmask_b32_e64 v76, v76, v186, s[38:39]
	v_cndmask_b32_e64 v189, v179, -v179, s[36:37]
	v_mov_b32_e32 v188, v77
	v_pk_mul_f32 v[188:189], v[38:39], v[188:189]
	s_nop 0
	v_add_f32_e32 v188, v188, v189
	v_cndmask_b32_e64 v77, v77, v188, s[38:39]
	v_cndmask_b32_e64 v187, v180, -v180, s[36:37]
	v_mov_b32_e32 v186, v78
	v_pk_mul_f32 v[186:187], v[32:33], v[186:187]
	s_nop 0
	v_add_f32_e32 v186, v186, v187
	v_cndmask_b32_e64 v78, v78, v186, s[38:39]
	v_cndmask_b32_e64 v189, v181, -v181, s[36:37]
	v_mov_b32_e32 v188, v79
	v_pk_mul_f32 v[188:189], v[34:35], v[188:189]
	s_nop 0
	v_add_f32_e32 v188, v188, v189
	v_cndmask_b32_e64 v79, v79, v188, s[38:39]
	v_cndmask_b32_e64 v187, v182, -v182, s[36:37]
	v_mov_b32_e32 v186, v72
	v_pk_mul_f32 v[186:187], v[28:29], v[186:187]
	s_nop 0
	v_add_f32_e32 v186, v186, v187
	v_cndmask_b32_e64 v72, v72, v186, s[38:39]
	v_cndmask_b32_e64 v189, v183, -v183, s[36:37]
	v_mov_b32_e32 v188, v73
	v_pk_mul_f32 v[188:189], v[30:31], v[188:189]
	s_nop 0
	v_add_f32_e32 v188, v188, v189
	v_cndmask_b32_e64 v73, v73, v188, s[38:39]
	v_cndmask_b32_e64 v187, v184, -v184, s[36:37]
	v_mov_b32_e32 v186, v74
	v_pk_mul_f32 v[186:187], v[24:25], v[186:187]
	s_nop 0
	v_add_f32_e32 v186, v186, v187
	v_cndmask_b32_e64 v74, v74, v186, s[38:39]
	v_cndmask_b32_e64 v189, v185, -v185, s[36:37]
	v_mov_b32_e32 v188, v75
	v_pk_mul_f32 v[188:189], v[26:27], v[188:189]
	s_nop 0
	v_add_f32_e32 v188, v188, v189
	v_cndmask_b32_e64 v75, v75, v188, s[38:39]

;     __device__ __forceinline__ void operator()(const f32x4 (&acc)[2][2][4][2], const Unit& u, int wr, int wc, int fr, int fq) const {
;     ...
;                 for (int bj = 0; bj < 2; ++bj) {
;                     f32x4 v0 = acc[ai][bj][m][0], v1 = acc[ai][bj][m][1];
;                     if (ropewave) {
;                         float v[8] = {v0[0], v0[1], v0[2], v0[3], v1[0], v1[1], v1[2], v1[3]};
; #pragma unroll
;                         for (int j = 0; j < 8; ++j) {
;                             const float p = __shfl_xor(v[j], 16);
;                             const float c = cs[j >> 1][(j & 1) * 2], s = cs[j >> 1][(j & 1) * 2 + 1];
;                             const float nv = v[j] * c + sgn * p * s;
;                             v[j] = (fq < 2) ? nv : v[j];
;                         }
;                         v0 = (f32x4){v[0], v[1], v[2], v[3]}; v1 = (f32x4){v[4], v[5], v[6], v[7]};
.LBB0_264:
	v_and_b32_e32 v206, 64, v237
	v_xor_b32_e32 v207, 16, v237
	v_add_u32_e32 v206, 64, v206
	v_cmp_lt_i32_e32 vcc, v207, v206
	s_nop 1
	v_cndmask_b32_e32 v207, v237, v207, vcc
	v_lshlrev_b32_e32 v207, 2, v207
	ds_bpermute_b32 v178, v207, v68
	ds_bpermute_b32 v179, v207, v69
	ds_bpermute_b32 v180, v207, v70
	ds_bpermute_b32 v181, v207, v71
	ds_bpermute_b32 v182, v207, v64
	ds_bpermute_b32 v183, v207, v65
	ds_bpermute_b32 v184, v207, v66
	ds_bpermute_b32 v185, v207, v67
	s_waitcnt lgkmcnt(0)
	v_cndmask_b32_e64 v187, v178, -v178, s[36:37]
	v_mov_b32_e32 v186, v68
	v_pk_mul_f32 v[186:187], v[36:37], v[186:187]
	s_nop 0
	v_add_f32_e32 v186, v186, v187
	v_cndmask_b32_e64 v68, v68, v186, s[38:39]
	v_cndmask_b32_e64 v189, v179, -v179, s[36:37]
	v_mov_b32_e32 v188, v69
	v_pk_mul_f32 v[188:189], v[38:39], v[188:189]
	s_nop 0
	v_add_f32_e32 v188, v188, v189
	v_cndmask_b32_e64 v69, v69, v188, s[38:39]
	v_cndmask_b32_e64 v187, v180, -v180, s[36:37]
	v_mov_b32_e32 v186, v70
	v_pk_mul_f32 v[186:187], v[32:33], v[186:187]
	s_nop 0
	v_add_f32_e32 v186, v186, v187
	v_cndmask_b32_e64 v70, v70, v186, s[38:39]
	v_cndmask_b32_e64 v189, v181, -v181, s[36:37]
	v_mov_b32_e32 v188, v71
	v_pk_mul_f32 v[188:189], v[34:35], v[188:189]
	s_nop 0
	v_add_f32_e32 v188, v188, v189
	v_cndmask_b32_e64 v71, v71, v188, s[38:39]
	v_cndmask_b32_e64 v187, v182, -v182, s[36:37]
	v_mov_b32_e32 v186, v64
	v_pk_mul_f32 v[186:187], v[28:29], v[186:187]
	s_nop 0
	v_add_f32_e32 v186, v186, v187
	v_cndmask_b32_e64 v64, v64, v186, s[38:39]
	v_cndmask_b32_e64 v189, v183, -v183, s[36:37]
	v_mov_b32_e32 v188, v65
	v_pk_mul_f32 v[188:189], v[30:31], v[188:189]
	s_nop 0
	v_add_f32_e32 v188, v188, v189
	v_cndmask_b32_e64 v65, v65, v188, s[38:39]
	v_cndmask_b32_e64 v187, v184, -v184, s[36:37]
	v_mov_b32_e32 v186, v66
	v_pk_mul_f32 v[186:187], v[24:25], v[186:187]
	s_nop 0
	v_add_f32_e32 v186, v186, v187
	v_cndmask_b32_e64 v66, v66, v186, s[38:39]
	v_cndmask_b32_e64 v189, v185, -v185, s[36:37]
	v_mov_b32_e32 v188, v67
	v_pk_mul_f32 v[188:189], v[26:27], v[188:189]
	s_nop 0
	v_add_f32_e32 v188, v188, v189
	v_cndmask_b32_e64 v67, v67, v188, s[38:39]

;     __device__ __forceinline__ void operator()(const f32x4 (&acc)[2][2][4][2], const Unit& u, int wr, int wc, int fr, int fq) const {
;     ...
;                 if (ropewave) { const float* rp = rope + (size_t)(row & 8191) * 16;
; #pragma unroll
;                     for (int k = 0; k < 4; ++k) cs[k] = *(const f32x4*)(rp + 4 * k); }
.LBB0_269:
	s_and_b64 vcc, exec, s[48:49]
	s_nop 0
	v_add_u32_e32 v64, 0x90, v154
	s_cbranch_vccnz .LBB0_277
	s_and_b64 vcc, exec, s[44:45]
	s_mov_b64 s[2:3], -1
	s_cbranch_vccz .LBB0_278

;     __device__ __forceinline__ void operator()(const f32x4 (&acc)[2][2][4][2], const Unit& u, int wr, int wc, int fr, int fq) const {
;     ...
;                 if (ropewave) { const float* rp = rope + (size_t)(row & 8191) * 16;
; #pragma unroll
;                     for (int k = 0; k < 4; ++k) cs[k] = *(const f32x4*)(rp + 4 * k); }
; #pragma unroll
;                 for (int bj = 0; bj < 2; ++bj) {
;                     f32x4 v0 = acc[ai][bj][m][0], v1 = acc[ai][bj][m][1];
;                     if (ropewave) {
;                         float v[8] = {v0[0], v0[1], v0[2], v0[3], v1[0], v1[1], v1[2], v1[3]};
; #pragma unroll
;                         for (int j = 0; j < 8; ++j) {
;                             const float p = __shfl_xor(v[j], 16);
;                             const float c = cs[j >> 1][(j & 1) * 2], s = cs[j >> 1][(j & 1) * 2 + 1];
;                             const float nv = v[j] * c + sgn * p * s;
;                             v[j] = (fq < 2) ? nv : v[j];
;                         }
;                         v0 = (f32x4){v[0], v[1], v[2], v[3]}; v1 = (f32x4){v[4], v[5], v[6], v[7]};
.LBB0_272:
	v_or_b32_e32 v206, 0xa0, v154
	v_lshlrev_b32_e32 v206, 6, v206
	v_and_b32_e32 v206, 0x7ffc0, v206
	global_load_dwordx4 v[36:39], v206, s[66:67]
	global_load_dwordx4 v[32:35], v206, s[66:67] offset:16
	global_load_dwordx4 v[28:31], v206, s[66:67] offset:32
	global_load_dwordx4 v[24:27], v206, s[66:67] offset:48
	v_and_b32_e32 v206, 64, v237
	v_xor_b32_e32 v207, 16, v237
	v_add_u32_e32 v206, 64, v206
	v_cmp_lt_i32_e32 vcc, v207, v206
	s_nop 1
	v_cndmask_b32_e32 v207, v237, v207, vcc
	v_lshlrev_b32_e32 v207, 2, v207
	ds_bpermute_b32 v178, v207, v60
	ds_bpermute_b32 v179, v207, v61
	ds_bpermute_b32 v180, v207, v62
	ds_bpermute_b32 v181, v207, v63
	ds_bpermute_b32 v182, v207, v56
	ds_bpermute_b32 v183, v207, v57
	ds_bpermute_b32 v184, v207, v58
	ds_bpermute_b32 v185, v207, v59
	s_waitcnt lgkmcnt(0)
	s_waitcnt vmcnt(6)
	v_cndmask_b32_e64 v187, v178, -v178, s[36:37]
	v_mov_b32_e32 v186, v60
	v_pk_mul_f32 v[186:187], v[202:203], v[186:187]
	s_nop 0
	v_add_f32_e32 v186, v186, v187
	v_cndmask_b32_e64 v60, v60, v186, s[38:39]
	v_cndmask_b32_e64 v189, v179, -v179, s[36:37]
	v_mov_b32_e32 v188, v61
	v_pk_mul_f32 v[188:189], v[204:205], v[188:189]
	s_nop 0
	v_add_f32_e32 v188, v188, v189
	v_cndmask_b32_e64 v61, v61, v188, s[38:39]
	v_cndmask_b32_e64 v187, v180, -v180, s[36:37]
	v_mov_b32_e32 v186, v62
	v_pk_mul_f32 v[186:187], v[198:199], v[186:187]
	s_nop 0
	v_add_f32_e32 v186, v186, v187
	v_cndmask_b32_e64 v62, v62, v186, s[38:39]
	v_cndmask_b32_e64 v189, v181, -v181, s[36:37]
	v_mov_b32_e32 v188, v63
	v_pk_mul_f32 v[188:189], v[200:201], v[188:189]
	s_nop 0
	v_add_f32_e32 v188, v188, v189
	v_cndmask_b32_e64 v63, v63, v188, s[38:39]
	v_cndmask_b32_e64 v187, v182, -v182, s[36:37]
	v_mov_b32_e32 v186, v56
	v_pk_mul_f32 v[186:187], v[194:195], v[186:187]
	s_nop 0
	v_add_f32_e32 v186, v186, v187
	v_cndmask_b32_e64 v56, v56, v186, s[38:39]
	v_cndmask_b32_e64 v189, v183, -v183, s[36:37]
	v_mov_b32_e32 v188, v57
	v_pk_mul_f32 v[188:189], v[196:197], v[188:189]
	s_nop 0
	v_add_f32_e32 v188, v188, v189
	v_cndmask_b32_e64 v57, v57, v188, s[38:39]
	v_cndmask_b32_e64 v187, v184, -v184, s[36:37]
	v_mov_b32_e32 v186, v58
	v_pk_mul_f32 v[186:187], v[190:191], v[186:187]
	s_nop 0
	v_add_f32_e32 v186, v186, v187
	v_cndmask_b32_e64 v58, v58, v186, s[38:39]
	v_cndmask_b32_e64 v189, v185, -v185, s[36:37]
	v_mov_b32_e32 v188, v59
	v_pk_mul_f32 v[188:189], v[192:193], v[188:189]
	s_nop 0
	v_add_f32_e32 v188, v188, v189
	v_cndmask_b32_e64 v59, v59, v188, s[38:39]

; __device__ __forceinline__ unsigned cvt_pk_bf16(float lo, float hi) { unsigned r; asm volatile("v_cvt_pk_bf16_f32 %0, %1, %2" : "=v"(r) : "v"(lo), "v"(hi)); return r; }
; #define WT_ST16(rsrc, byteoff, v) __builtin_amdgcn_raw_buffer_store_b128((v), (rsrc), (unsigned)(byteoff), 0, 16)
;     __device__ __forceinline__ void operator()(const f32x4 (&acc)[2][2][4][2], const Unit& u, int wr, int wc, int fr, int fq) const {
;     ...
; #pragma unroll
;                 for (int bj = 0; bj < 2; ++bj) {
;                     f32x4 v0 = acc[ai][bj][m][0], v1 = acc[ai][bj][m][1];
;                     if (ropewave) {
;                         float v[8] = {v0[0], v0[1], v0[2], v0[3], v1[0], v1[1], v1[2], v1[3]};
; #pragma unroll
;                         for (int j = 0; j < 8; ++j) {
;                             const float p = __shfl_xor(v[j], 16);
;                             const float c = cs[j >> 1][(j & 1) * 2], s = cs[j >> 1][(j & 1) * 2 + 1];
;                             const float nv = v[j] * c + sgn * p * s;
;                             v[j] = (fq < 2) ? nv : v[j];
;                         }
;                         v0 = (f32x4){v[0], v[1], v[2], v[3]}; v1 = (f32x4){v[4], v[5], v[6], v[7]};
;                     }
;                     v0 = v0 * scr; v1 = v1 * scr;
;                     u32x4 w; w.x = cvt_pk_bf16(v0[0], v0[1]); w.y = cvt_pk_bf16(v0[2], v0[3]); w.z = cvt_pk_bf16(v1[0], v1[1]); w.w = cvt_pk_bf16(v1[2], v1[3]);
;                     if (pub) WT_ST16(orsrc, ((size_t)row * 3584 + col0 + bj * HALF) * 2, w); else *(u32x4*)(rowp + bj * HALF) = w;
.LBB0_282:
	v_and_b32_e32 v206, 64, v237
	v_xor_b32_e32 v207, 16, v237
	v_add_u32_e32 v206, 64, v206
	v_cmp_lt_i32_e32 vcc, v207, v206
	s_nop 1
	v_cndmask_b32_e32 v207, v237, v207, vcc
	v_lshlrev_b32_e32 v207, 2, v207
	ds_bpermute_b32 v178, v207, v52
	ds_bpermute_b32 v179, v207, v53
	ds_bpermute_b32 v180, v207, v54
	ds_bpermute_b32 v181, v207, v55
	ds_bpermute_b32 v182, v207, v48
	ds_bpermute_b32 v183, v207, v49
	ds_bpermute_b32 v184, v207, v50
	ds_bpermute_b32 v185, v207, v51
	s_waitcnt lgkmcnt(0)
	v_cndmask_b32_e64 v187, v178, -v178, s[36:37]
	v_mov_b32_e32 v186, v52
	v_pk_mul_f32 v[186:187], v[202:203], v[186:187]
	s_nop 0
	v_add_f32_e32 v186, v186, v187
	v_cndmask_b32_e64 v52, v52, v186, s[38:39]
	v_cndmask_b32_e64 v189, v179, -v179, s[36:37]
	v_mov_b32_e32 v188, v53
	v_pk_mul_f32 v[188:189], v[204:205], v[188:189]
	s_nop 0
	v_add_f32_e32 v188, v188, v189
	v_cndmask_b32_e64 v53, v53, v188, s[38:39]
	v_cndmask_b32_e64 v187, v180, -v180, s[36:37]
	v_mov_b32_e32 v186, v54
	v_pk_mul_f32 v[186:187], v[198:199], v[186:187]
	s_nop 0
	v_add_f32_e32 v186, v186, v187
	v_cndmask_b32_e64 v54, v54, v186, s[38:39]
	v_cndmask_b32_e64 v189, v181, -v181, s[36:37]
	v_mov_b32_e32 v188, v55
	v_pk_mul_f32 v[188:189], v[200:201], v[188:189]
	s_nop 0
	v_add_f32_e32 v188, v188, v189
	v_cndmask_b32_e64 v55, v55, v188, s[38:39]
	v_cndmask_b32_e64 v187, v182, -v182, s[36:37]
	v_mov_b32_e32 v186, v48
	v_pk_mul_f32 v[186:187], v[194:195], v[186:187]
	s_nop 0
	v_add_f32_e32 v186, v186, v187
	v_cndmask_b32_e64 v48, v48, v186, s[38:39]
	v_cndmask_b32_e64 v189, v183, -v183, s[36:37]
	v_mov_b32_e32 v188, v49
	v_pk_mul_f32 v[188:189], v[196:197], v[188:189]
	s_nop 0
	v_add_f32_e32 v188, v188, v189
	v_cndmask_b32_e64 v49, v49, v188, s[38:39]
	v_cndmask_b32_e64 v187, v184, -v184, s[36:37]
	v_mov_b32_e32 v186, v50
	v_pk_mul_f32 v[186:187], v[190:191], v[186:187]
	s_nop 0
	v_add_f32_e32 v186, v186, v187
	v_cndmask_b32_e64 v50, v50, v186, s[38:39]
	v_cndmask_b32_e64 v189, v185, -v185, s[36:37]
	v_mov_b32_e32 v188, v51
	v_pk_mul_f32 v[188:189], v[192:193], v[188:189]
	s_nop 0
	v_add_f32_e32 v188, v188, v189
	v_cndmask_b32_e64 v51, v51, v188, s[38:39]

;     __device__ __forceinline__ void operator()(const f32x4 (&acc)[2][2][4][2], const Unit& u, int wr, int wc, int fr, int fq) const {
;     ...
;                 const int row = row0 + ai * HALF + m * 16;
;                 bf16_t* rowp = O + (size_t)row * 3584 + col0;
;                 const float scr = rowss ? sc * __builtin_amdgcn_rsqf(rsv[ai][m] * (1.0f / 1024.0f) + 1e-6f) : sc;
;                 f32x4 cs[4];
;                 if (ropewave) { const float* rp = rope + (size_t)(row & 8191) * 16;
; #pragma unroll
;                     for (int k = 0; k < 4; ++k) cs[k] = *(const f32x4*)(rp + 4 * k); }
.LBB0_287:
	s_and_b64 vcc, exec, s[48:49]
	s_nop 0
	v_add_u32_e32 v48, 0xa0, v154
	s_cbranch_vccnz .LBB0_295
	s_and_b64 vcc, exec, s[44:45]
	s_mov_b64 s[2:3], -1
	s_cbranch_vccz .LBB0_296

;     __device__ __forceinline__ void operator()(const f32x4 (&acc)[2][2][4][2], const Unit& u, int wr, int wc, int fr, int fq) const {
;     ...
;                 if (ropewave) { const float* rp = rope + (size_t)(row & 8191) * 16;
; #pragma unroll
;                     for (int k = 0; k < 4; ++k) cs[k] = *(const f32x4*)(rp + 4 * k); }
; #pragma unroll
;                 for (int bj = 0; bj < 2; ++bj) {
;                     f32x4 v0 = acc[ai][bj][m][0], v1 = acc[ai][bj][m][1];
;                     if (ropewave) {
;                         float v[8] = {v0[0], v0[1], v0[2], v0[3], v1[0], v1[1], v1[2], v1[3]};
; #pragma unroll
;                         for (int j = 0; j < 8; ++j) {
;                             const float p = __shfl_xor(v[j], 16);
;                             const float c = cs[j >> 1][(j & 1) * 2], s = cs[j >> 1][(j & 1) * 2 + 1];
;                             const float nv = v[j] * c + sgn * p * s;
;                             v[j] = (fq < 2) ? nv : v[j];
;                         }
;                         v0 = (f32x4){v[0], v[1], v[2], v[3]}; v1 = (f32x4){v[4], v[5], v[6], v[7]};
.LBB0_290:
	v_or_b32_e32 v206, 0xb0, v154
	v_lshlrev_b32_e32 v206, 6, v206
	v_and_b32_e32 v206, 0x7ffc0, v206
	global_load_dwordx4 v[202:205], v206, s[66:67]
	global_load_dwordx4 v[198:201], v206, s[66:67] offset:16
	global_load_dwordx4 v[194:197], v206, s[66:67] offset:32
	global_load_dwordx4 v[190:193], v206, s[66:67] offset:48
	v_and_b32_e32 v206, 64, v237
	v_xor_b32_e32 v207, 16, v237
	v_add_u32_e32 v206, 64, v206
	v_cmp_lt_i32_e32 vcc, v207, v206
	s_nop 1
	v_cndmask_b32_e32 v207, v237, v207, vcc
	v_lshlrev_b32_e32 v207, 2, v207
	ds_bpermute_b32 v178, v207, v44
	ds_bpermute_b32 v179, v207, v45
	ds_bpermute_b32 v180, v207, v46
	ds_bpermute_b32 v181, v207, v47
	ds_bpermute_b32 v182, v207, v40
	ds_bpermute_b32 v183, v207, v41
	ds_bpermute_b32 v184, v207, v42
	ds_bpermute_b32 v185, v207, v43
	s_waitcnt lgkmcnt(0)
	s_waitcnt vmcnt(6)
	v_cndmask_b32_e64 v187, v178, -v178, s[36:37]
	v_mov_b32_e32 v186, v44
	v_pk_mul_f32 v[186:187], v[36:37], v[186:187]
	s_nop 0
	v_add_f32_e32 v186, v186, v187
	v_cndmask_b32_e64 v44, v44, v186, s[38:39]
	v_cndmask_b32_e64 v189, v179, -v179, s[36:37]
	v_mov_b32_e32 v188, v45
	v_pk_mul_f32 v[188:189], v[38:39], v[188:189]
	s_nop 0
	v_add_f32_e32 v188, v188, v189
	v_cndmask_b32_e64 v45, v45, v188, s[38:39]
	v_cndmask_b32_e64 v187, v180, -v180, s[36:37]
	v_mov_b32_e32 v186, v46
	v_pk_mul_f32 v[186:187], v[32:33], v[186:187]
	s_nop 0
	v_add_f32_e32 v186, v186, v187
	v_cndmask_b32_e64 v46, v46, v186, s[38:39]
	v_cndmask_b32_e64 v189, v181, -v181, s[36:37]
	v_mov_b32_e32 v188, v47
	v_pk_mul_f32 v[188:189], v[34:35], v[188:189]
	s_nop 0
	v_add_f32_e32 v188, v188, v189
	v_cndmask_b32_e64 v47, v47, v188, s[38:39]
	v_cndmask_b32_e64 v187, v182, -v182, s[36:37]
	v_mov_b32_e32 v186, v40
	v_pk_mul_f32 v[186:187], v[28:29], v[186:187]
	s_nop 0
	v_add_f32_e32 v186, v186, v187
	v_cndmask_b32_e64 v40, v40, v186, s[38:39]
	v_cndmask_b32_e64 v189, v183, -v183, s[36:37]
	v_mov_b32_e32 v188, v41
	v_pk_mul_f32 v[188:189], v[30:31], v[188:189]
	s_nop 0
	v_add_f32_e32 v188, v188, v189
	v_cndmask_b32_e64 v41, v41, v188, s[38:39]
	v_cndmask_b32_e64 v187, v184, -v184, s[36:37]
	v_mov_b32_e32 v186, v42
	v_pk_mul_f32 v[186:187], v[24:25], v[186:187]
	s_nop 0
	v_add_f32_e32 v186, v186, v187
	v_cndmask_b32_e64 v42, v42, v186, s[38:39]
	v_cndmask_b32_e64 v189, v185, -v185, s[36:37]
	v_mov_b32_e32 v188, v43
	v_pk_mul_f32 v[188:189], v[26:27], v[188:189]
	s_nop 0
	v_add_f32_e32 v188, v188, v189
	v_cndmask_b32_e64 v43, v43, v188, s[38:39]

; __device__ __forceinline__ unsigned cvt_pk_bf16(float lo, float hi) { unsigned r; asm volatile("v_cvt_pk_bf16_f32 %0, %1, %2" : "=v"(r) : "v"(lo), "v"(hi)); return r; }
; #define WT_ST16(rsrc, byteoff, v) __builtin_amdgcn_raw_buffer_store_b128((v), (rsrc), (unsigned)(byteoff), 0, 16)
;     __device__ __forceinline__ void operator()(const f32x4 (&acc)[2][2][4][2], const Unit& u, int wr, int wc, int fr, int fq) const {
;     ...
; #pragma unroll
;                 for (int bj = 0; bj < 2; ++bj) {
;                     f32x4 v0 = acc[ai][bj][m][0], v1 = acc[ai][bj][m][1];
;                     if (ropewave) {
;                         float v[8] = {v0[0], v0[1], v0[2], v0[3], v1[0], v1[1], v1[2], v1[3]};
; #pragma unroll
;                         for (int j = 0; j < 8; ++j) {
;                             const float p = __shfl_xor(v[j], 16);
;                             const float c = cs[j >> 1][(j & 1) * 2], s = cs[j >> 1][(j & 1) * 2 + 1];
;                             const float nv = v[j] * c + sgn * p * s;
;                             v[j] = (fq < 2) ? nv : v[j];
;                         }
;                         v0 = (f32x4){v[0], v[1], v[2], v[3]}; v1 = (f32x4){v[4], v[5], v[6], v[7]};
;                     }
;                     v0 = v0 * scr; v1 = v1 * scr;
;                     u32x4 w; w.x = cvt_pk_bf16(v0[0], v0[1]); w.y = cvt_pk_bf16(v0[2], v0[3]); w.z = cvt_pk_bf16(v1[0], v1[1]); w.w = cvt_pk_bf16(v1[2], v1[3]);
;                     if (pub) WT_ST16(orsrc, ((size_t)row * 3584 + col0 + bj * HALF) * 2, w); else *(u32x4*)(rowp + bj * HALF) = w;
.LBB0_300:
	v_and_b32_e32 v206, 64, v237
	v_xor_b32_e32 v207, 16, v237
	v_add_u32_e32 v206, 64, v206
	v_cmp_lt_i32_e32 vcc, v207, v206
	s_nop 1
	v_cndmask_b32_e32 v207, v237, v207, vcc
	v_lshlrev_b32_e32 v207, 2, v207
	ds_bpermute_b32 v178, v207, v20
	ds_bpermute_b32 v179, v207, v21
	ds_bpermute_b32 v180, v207, v22
	ds_bpermute_b32 v181, v207, v23
	ds_bpermute_b32 v182, v207, v16
	ds_bpermute_b32 v183, v207, v17
	ds_bpermute_b32 v184, v207, v18
	ds_bpermute_b32 v185, v207, v19
	s_waitcnt lgkmcnt(0)
	v_cndmask_b32_e64 v187, v178, -v178, s[36:37]
	v_mov_b32_e32 v186, v20
	v_pk_mul_f32 v[186:187], v[36:37], v[186:187]
	s_nop 0
	v_add_f32_e32 v186, v186, v187
	v_cndmask_b32_e64 v20, v20, v186, s[38:39]
	v_cndmask_b32_e64 v189, v179, -v179, s[36:37]
	v_mov_b32_e32 v188, v21
	v_pk_mul_f32 v[188:189], v[38:39], v[188:189]
	s_nop 0
	v_add_f32_e32 v188, v188, v189
	v_cndmask_b32_e64 v21, v21, v188, s[38:39]
	v_cndmask_b32_e64 v187, v180, -v180, s[36:37]
	v_mov_b32_e32 v186, v22
	v_pk_mul_f32 v[186:187], v[32:33], v[186:187]
	s_nop 0
	v_add_f32_e32 v186, v186, v187
	v_cndmask_b32_e64 v22, v22, v186, s[38:39]
	v_cndmask_b32_e64 v189, v181, -v181, s[36:37]
	v_mov_b32_e32 v188, v23
	v_pk_mul_f32 v[188:189], v[34:35], v[188:189]
	s_nop 0
	v_add_f32_e32 v188, v188, v189
	v_cndmask_b32_e64 v23, v23, v188, s[38:39]
	v_cndmask_b32_e64 v187, v182, -v182, s[36:37]
	v_mov_b32_e32 v186, v16
	v_pk_mul_f32 v[186:187], v[28:29], v[186:187]
	s_nop 0
	v_add_f32_e32 v186, v186, v187
	v_cndmask_b32_e64 v16, v16, v186, s[38:39]
	v_cndmask_b32_e64 v189, v183, -v183, s[36:37]
	v_mov_b32_e32 v188, v17
	v_pk_mul_f32 v[188:189], v[30:31], v[188:189]
	s_nop 0
	v_add_f32_e32 v188, v188, v189
	v_cndmask_b32_e64 v17, v17, v188, s[38:39]
	v_cndmask_b32_e64 v187, v184, -v184, s[36:37]
	v_mov_b32_e32 v186, v18
	v_pk_mul_f32 v[186:187], v[24:25], v[186:187]
	s_nop 0
	v_add_f32_e32 v186, v186, v187
	v_cndmask_b32_e64 v18, v18, v186, s[38:39]
	v_cndmask_b32_e64 v189, v185, -v185, s[36:37]
	v_mov_b32_e32 v188, v19
	v_pk_mul_f32 v[188:189], v[26:27], v[188:189]
	s_nop 0
	v_add_f32_e32 v188, v188, v189
	v_cndmask_b32_e64 v19, v19, v188, s[38:39]

;     __device__ __forceinline__ void operator()(const f32x4 (&acc)[2][2][4][2], const Unit& u, int wr, int wc, int fr, int fq) const {
;     ...
;                 const int row = row0 + ai * HALF + m * 16;
;                 bf16_t* rowp = O + (size_t)row * 3584 + col0;
;                 const float scr = rowss ? sc * __builtin_amdgcn_rsqf(rsv[ai][m] * (1.0f / 1024.0f) + 1e-6f) : sc;
;                 f32x4 cs[4];
;                 if (ropewave) { const float* rp = rope + (size_t)(row & 8191) * 16;
; #pragma unroll
;                     for (int k = 0; k < 4; ++k) cs[k] = *(const f32x4*)(rp + 4 * k); }
.LBB0_305:
	s_and_b64 vcc, exec, s[48:49]
	s_nop 0
	v_add_u32_e32 v16, 0xb0, v154
	s_cbranch_vccnz .LBB0_313
	s_and_b64 vcc, exec, s[44:45]
	s_mov_b64 s[2:3], -1
	s_cbranch_vccz .LBB0_314

;     __device__ __forceinline__ void operator()(const f32x4 (&acc)[2][2][4][2], const Unit& u, int wr, int wc, int fr, int fq) const {
;     ...
;                 if (ropewave) { const float* rp = rope + (size_t)(row & 8191) * 16;
; #pragma unroll
;                     for (int k = 0; k < 4; ++k) cs[k] = *(const f32x4*)(rp + 4 * k); }
; #pragma unroll
;                 for (int bj = 0; bj < 2; ++bj) {
;                     f32x4 v0 = acc[ai][bj][m][0], v1 = acc[ai][bj][m][1];
;                     if (ropewave) {
;                         float v[8] = {v0[0], v0[1], v0[2], v0[3], v1[0], v1[1], v1[2], v1[3]};
; #pragma unroll
;                         for (int j = 0; j < 8; ++j) {
;                             const float p = __shfl_xor(v[j], 16);
;                             const float c = cs[j >> 1][(j & 1) * 2], s = cs[j >> 1][(j & 1) * 2 + 1];
;                             const float nv = v[j] * c + sgn * p * s;
;                             v[j] = (fq < 2) ? nv : v[j];
;                         }
;                         v0 = (f32x4){v[0], v[1], v[2], v[3]}; v1 = (f32x4){v[4], v[5], v[6], v[7]};
.LBB0_308:
	v_and_b32_e32 v206, 64, v237
	v_xor_b32_e32 v207, 16, v237
	v_add_u32_e32 v206, 64, v206
	v_cmp_lt_i32_e32 vcc, v207, v206
	s_nop 1
	v_cndmask_b32_e32 v207, v237, v207, vcc
	v_lshlrev_b32_e32 v207, 2, v207
	ds_bpermute_b32 v178, v207, v12
	ds_bpermute_b32 v179, v207, v13
	ds_bpermute_b32 v180, v207, v14
	ds_bpermute_b32 v181, v207, v15
	ds_bpermute_b32 v182, v207, v8
	ds_bpermute_b32 v183, v207, v9
	ds_bpermute_b32 v184, v207, v10
	ds_bpermute_b32 v185, v207, v11
	s_waitcnt lgkmcnt(0)
	s_waitcnt vmcnt(2)
	v_cndmask_b32_e64 v187, v178, -v178, s[36:37]
	v_mov_b32_e32 v186, v12
	v_pk_mul_f32 v[186:187], v[202:203], v[186:187]
	s_nop 0
	v_add_f32_e32 v186, v186, v187
	v_cndmask_b32_e64 v12, v12, v186, s[38:39]
	v_cndmask_b32_e64 v189, v179, -v179, s[36:37]
	v_mov_b32_e32 v188, v13
	v_pk_mul_f32 v[188:189], v[204:205], v[188:189]
	s_nop 0
	v_add_f32_e32 v188, v188, v189
	v_cndmask_b32_e64 v13, v13, v188, s[38:39]
	v_cndmask_b32_e64 v187, v180, -v180, s[36:37]
	v_mov_b32_e32 v186, v14
	v_pk_mul_f32 v[186:187], v[198:199], v[186:187]
	s_nop 0
	v_add_f32_e32 v186, v186, v187
	v_cndmask_b32_e64 v14, v14, v186, s[38:39]
	v_cndmask_b32_e64 v189, v181, -v181, s[36:37]
	v_mov_b32_e32 v188, v15
	v_pk_mul_f32 v[188:189], v[200:201], v[188:189]
	s_nop 0
	v_add_f32_e32 v188, v188, v189
	v_cndmask_b32_e64 v15, v15, v188, s[38:39]
	v_cndmask_b32_e64 v187, v182, -v182, s[36:37]
	v_mov_b32_e32 v186, v8
	v_pk_mul_f32 v[186:187], v[194:195], v[186:187]
	s_nop 0
	v_add_f32_e32 v186, v186, v187
	v_cndmask_b32_e64 v8, v8, v186, s[38:39]
	v_cndmask_b32_e64 v189, v183, -v183, s[36:37]
	v_mov_b32_e32 v188, v9
	v_pk_mul_f32 v[188:189], v[196:197], v[188:189]
	s_nop 0
	v_add_f32_e32 v188, v188, v189
	v_cndmask_b32_e64 v9, v9, v188, s[38:39]
	v_cndmask_b32_e64 v187, v184, -v184, s[36:37]
	v_mov_b32_e32 v186, v10
	v_pk_mul_f32 v[186:187], v[190:191], v[186:187]
	s_nop 0
	v_add_f32_e32 v186, v186, v187
	v_cndmask_b32_e64 v10, v10, v186, s[38:39]
	v_cndmask_b32_e64 v189, v185, -v185, s[36:37]
	v_mov_b32_e32 v188, v11
	v_pk_mul_f32 v[188:189], v[192:193], v[188:189]
	s_nop 0
	v_add_f32_e32 v188, v188, v189
	v_cndmask_b32_e64 v11, v11, v188, s[38:39]

; __device__ __forceinline__ unsigned cvt_pk_bf16(float lo, float hi) { unsigned r; asm volatile("v_cvt_pk_bf16_f32 %0, %1, %2" : "=v"(r) : "v"(lo), "v"(hi)); return r; }
; #define WT_ST16(rsrc, byteoff, v) __builtin_amdgcn_raw_buffer_store_b128((v), (rsrc), (unsigned)(byteoff), 0, 16)
;     __device__ __forceinline__ void operator()(const f32x4 (&acc)[2][2][4][2], const Unit& u, int wr, int wc, int fr, int fq) const {
;     ...
; #pragma unroll
;                 for (int bj = 0; bj < 2; ++bj) {
;                     f32x4 v0 = acc[ai][bj][m][0], v1 = acc[ai][bj][m][1];
;                     if (ropewave) {
;                         float v[8] = {v0[0], v0[1], v0[2], v0[3], v1[0], v1[1], v1[2], v1[3]};
; #pragma unroll
;                         for (int j = 0; j < 8; ++j) {
;                             const float p = __shfl_xor(v[j], 16);
;                             const float c = cs[j >> 1][(j & 1) * 2], s = cs[j >> 1][(j & 1) * 2 + 1];
;                             const float nv = v[j] * c + sgn * p * s;
;                             v[j] = (fq < 2) ? nv : v[j];
;                         }
;                         v0 = (f32x4){v[0], v[1], v[2], v[3]}; v1 = (f32x4){v[4], v[5], v[6], v[7]};
;                     }
;                     v0 = v0 * scr; v1 = v1 * scr;
;                     u32x4 w; w.x = cvt_pk_bf16(v0[0], v0[1]); w.y = cvt_pk_bf16(v0[2], v0[3]); w.z = cvt_pk_bf16(v1[0], v1[1]); w.w = cvt_pk_bf16(v1[2], v1[3]);
;                     if (pub) WT_ST16(orsrc, ((size_t)row * 3584 + col0 + bj * HALF) * 2, w); else *(u32x4*)(rowp + bj * HALF) = w;
.LBB0_318:
	v_and_b32_e32 v206, 64, v237
	v_xor_b32_e32 v207, 16, v237
	v_add_u32_e32 v206, 64, v206
	v_cmp_lt_i32_e32 vcc, v207, v206
	s_nop 1
	v_cndmask_b32_e32 v207, v237, v207, vcc
	v_lshlrev_b32_e32 v207, 2, v207
	ds_bpermute_b32 v178, v207, v4
	ds_bpermute_b32 v179, v207, v5
	ds_bpermute_b32 v180, v207, v6
	ds_bpermute_b32 v181, v207, v7
	ds_bpermute_b32 v182, v207, v0
	ds_bpermute_b32 v183, v207, v1
	ds_bpermute_b32 v184, v207, v2
	ds_bpermute_b32 v185, v207, v3
	s_waitcnt lgkmcnt(0)
	v_cndmask_b32_e64 v187, v178, -v178, s[36:37]
	v_mov_b32_e32 v186, v4
	v_pk_mul_f32 v[186:187], v[202:203], v[186:187]
	s_nop 0
	v_add_f32_e32 v186, v186, v187
	v_cndmask_b32_e64 v4, v4, v186, s[38:39]
	v_cndmask_b32_e64 v189, v179, -v179, s[36:37]
	v_mov_b32_e32 v188, v5
	v_pk_mul_f32 v[188:189], v[204:205], v[188:189]
	s_nop 0
	v_add_f32_e32 v188, v188, v189
	v_cndmask_b32_e64 v5, v5, v188, s[38:39]
	v_cndmask_b32_e64 v187, v180, -v180, s[36:37]
	v_mov_b32_e32 v186, v6
	v_pk_mul_f32 v[186:187], v[198:199], v[186:187]
	s_nop 0
	v_add_f32_e32 v186, v186, v187
	v_cndmask_b32_e64 v6, v6, v186, s[38:39]
	v_cndmask_b32_e64 v189, v181, -v181, s[36:37]
	v_mov_b32_e32 v188, v7
	v_pk_mul_f32 v[188:189], v[200:201], v[188:189]
	s_nop 0
	v_add_f32_e32 v188, v188, v189
	v_cndmask_b32_e64 v7, v7, v188, s[38:39]
	v_cndmask_b32_e64 v187, v182, -v182, s[36:37]
	v_mov_b32_e32 v186, v0
	v_pk_mul_f32 v[186:187], v[194:195], v[186:187]
	s_nop 0
	v_add_f32_e32 v186, v186, v187
	v_cndmask_b32_e64 v0, v0, v186, s[38:39]
	v_cndmask_b32_e64 v189, v183, -v183, s[36:37]
	v_mov_b32_e32 v188, v1
	v_pk_mul_f32 v[188:189], v[196:197], v[188:189]
	s_nop 0
	v_add_f32_e32 v188, v188, v189
	v_cndmask_b32_e64 v1, v1, v188, s[38:39]
	v_cndmask_b32_e64 v187, v184, -v184, s[36:37]
	v_mov_b32_e32 v186, v2
	v_pk_mul_f32 v[186:187], v[190:191], v[186:187]
	s_nop 0
	v_add_f32_e32 v186, v186, v187
	v_cndmask_b32_e64 v2, v2, v186, s[38:39]
	v_cndmask_b32_e64 v189, v185, -v185, s[36:37]
	v_mov_b32_e32 v188, v3
	v_pk_mul_f32 v[188:189], v[192:193], v[188:189]
	s_nop 0
	v_add_f32_e32 v188, v188, v189
	v_cndmask_b32_e64 v3, v3, v188, s[38:39]
